# EPI1 rs loads issued above next-tile LDS-DMA prefetch, uniform vmcnt(15) via 8 dummy loads on last-tile path
# speedup vs baseline: 1.0208x; 1.0013x over previous
; __device__ __forceinline__ unsigned pack2(float a, float b) { f32v2_t v = {a, b}; bf16v2_t r = __builtin_convertvector(v, bf16v2_t); return __builtin_bit_cast(unsigned, r); }
; template <int EPI, int N, int K>
; __device__ __forceinline__ void gemm_phase(const KP& p, int l, const bfr* A, const bfr* Bt) {
;     ...
;         for (int m = 0; m < 4; ++m) {
;           int row = erow + ai * HM + wr * 64 + m * 16 + fr;
;           const float r = rs[row];
;           const float nrl = -1.44269504f * r, r2 = r * r;
;           u32x4 pk;
; #pragma unroll
;           for (int bj = 0; bj < 2; ++bj)
; #pragma unroll
;             for (int jj = 0; jj < 2; ++jj) {
;               f32v2_t g2 = {acc[ai][bj][m][0][2 * jj], acc[ai][bj][m][0][2 * jj + 1]};
;               f32v2_t u2 = {acc[ai][bj][m][1][2 * jj], acc[ai][bj][m][1][2 * jj + 1]};
;               f32v2_t t2 = g2 * nrl;
;               f32v2_t e2 = {__builtin_amdgcn_exp2f(t2.x), __builtin_amdgcn_exp2f(t2.y)};
;               f32v2_t d2 = e2 + 1.0f;
;               f32v2_t rc = {__builtin_amdgcn_rcpf(d2.x), __builtin_amdgcn_rcpf(d2.y)};
;               f32v2_t o2 = (g2 * u2) * r2 * rc;
;               pk[bj * 2 + jj] = pack2(o2.x, o2.y);
;             }
;           *(u32x4*)(act + (size_t)row * DFF + (ecol >> 1) + wc * 32 + fq * 8) = pk;
.LBB0_235:
	v_add_u32_e32 v134, s76, v147
	v_ashrrev_i32_e32 v135, 31, v134
	v_lshl_add_u64 v[166:167], v[134:135], 2, s[46:47]
	v_pk_mul_f32 v[128:129], v[124:125], v[128:129]
	s_ashr_i32 s2, s78, 1
	v_pk_mul_f32 v[120:121], v[116:117], v[120:121]
	s_ashr_i32 s3, s2, 31
	v_lshl_add_u64 v[132:133], s[2:3], 1, v[130:131]
	s_movk_i32 s14, 0x1600
	v_pk_mul_f32 v[112:113], v[108:109], v[112:113]
	v_pk_mul_f32 v[104:105], v[100:101], v[104:105]
	v_pk_mul_f32 v[96:97], v[92:93], v[96:97]
	v_pk_mul_f32 v[88:89], v[84:85], v[88:89]
	v_pk_mul_f32 v[80:81], v[76:77], v[80:81]
	v_pk_mul_f32 v[72:73], v[68:69], v[72:73]
	v_pk_mul_f32 v[64:65], v[60:61], v[64:65]
	v_pk_mul_f32 v[56:57], v[52:53], v[56:57]
	v_pk_mul_f32 v[48:49], v[44:45], v[48:49]
	v_pk_mul_f32 v[40:41], v[36:37], v[40:41]
	v_pk_mul_f32 v[32:33], v[28:29], v[32:33]
	v_pk_mul_f32 v[24:25], v[20:21], v[24:25]
	v_pk_mul_f32 v[16:17], v[12:13], v[16:17]
	v_pk_mul_f32 v[8:9], v[4:5], v[8:9]
	s_and_b64 vcc, exec, s[50:51]
	s_mov_b32 s76, s74
	s_mov_b32 s78, s52
	s_waitcnt vmcnt(15)
	v_mov_b32_e32 v135, v222
	v_mul_f32_e32 v0, 0xbfb8aa3b, v135
	v_pk_mul_f32 v[168:169], v[122:123], v[0:1] op_sel_hi:[1,0]
	v_pk_mul_f32 v[124:125], v[124:125], v[0:1] op_sel_hi:[1,0]
	v_exp_f32_e32 v168, v168
	v_exp_f32_e32 v169, v169
	v_exp_f32_e32 v124, v124
	v_exp_f32_e32 v125, v125
	v_mul_f32_e32 v166, v135, v135
	v_pk_add_f32 v[168:169], v[168:169], 1.0 op_sel_hi:[1,0]
	v_pk_mul_f32 v[122:123], v[122:123], v[126:127]
	v_pk_add_f32 v[124:125], v[124:125], 1.0 op_sel_hi:[1,0]
	v_rcp_f32_e32 v168, v168
	v_rcp_f32_e32 v169, v169
	v_rcp_f32_e32 v124, v124
	v_rcp_f32_e32 v125, v125
	v_pk_mul_f32 v[122:123], v[122:123], v[166:167] op_sel_hi:[1,0]
	v_pk_mul_f32 v[126:127], v[128:129], v[166:167] op_sel_hi:[1,0]
	v_pk_mul_f32 v[122:123], v[122:123], v[168:169]
	v_pk_mul_f32 v[124:125], v[126:127], v[124:125]
	v_cvt_pk_bf16_f32 v122, v122, v123
	v_cvt_pk_bf16_f32 v123, v124, v125
	v_pk_mul_f32 v[124:125], v[114:115], v[0:1] op_sel_hi:[1,0]
	v_pk_mul_f32 v[114:115], v[114:115], v[118:119]
	v_exp_f32_e32 v124, v124
	v_exp_f32_e32 v125, v125
	v_pk_mul_f32 v[114:115], v[114:115], v[166:167] op_sel_hi:[1,0]
	v_pk_add_f32 v[124:125], v[124:125], 1.0 op_sel_hi:[1,0]
	s_nop 0
	v_rcp_f32_e32 v124, v124
	v_rcp_f32_e32 v125, v125
	s_nop 0
	v_pk_mul_f32 v[114:115], v[114:115], v[124:125]
	s_nop 0
	v_cvt_pk_bf16_f32 v124, v114, v115
	v_pk_mul_f32 v[114:115], v[116:117], v[0:1] op_sel_hi:[1,0]
	v_pk_mul_f32 v[116:117], v[120:121], v[166:167] op_sel_hi:[1,0]
	v_exp_f32_e32 v114, v114
	v_exp_f32_e32 v115, v115
	s_nop 0
	v_pk_add_f32 v[114:115], v[114:115], 1.0 op_sel_hi:[1,0]
	s_nop 0
	v_rcp_f32_e32 v114, v114
	v_rcp_f32_e32 v115, v115
	s_nop 0
	v_pk_mul_f32 v[114:115], v[116:117], v[114:115]
	s_nop 0
	v_cvt_pk_bf16_f32 v125, v114, v115
	v_mad_i64_i32 v[114:115], s[2:3], v134, s14, v[132:133]
	global_store_dwordx4 v[114:115], v[122:125], off
	v_or_b32_e32 v114, 16, v134
	v_ashrrev_i32_e32 v115, 31, v114
	v_lshl_add_u64 v[116:117], v[114:115], 2, s[46:47]
	s_waitcnt vmcnt(15)
	v_mov_b32_e32 v115, v223
	v_mul_f32_e32 v0, 0xbfb8aa3b, v115
	v_pk_mul_f32 v[118:119], v[106:107], v[0:1] op_sel_hi:[1,0]
	v_pk_mul_f32 v[108:109], v[108:109], v[0:1] op_sel_hi:[1,0]
	v_exp_f32_e32 v118, v118
	v_exp_f32_e32 v119, v119
	v_exp_f32_e32 v108, v108
	v_exp_f32_e32 v109, v109
	v_mul_f32_e32 v116, v115, v115
	v_pk_add_f32 v[118:119], v[118:119], 1.0 op_sel_hi:[1,0]
	v_pk_mul_f32 v[106:107], v[106:107], v[110:111]
	v_pk_add_f32 v[108:109], v[108:109], 1.0 op_sel_hi:[1,0]
	v_rcp_f32_e32 v118, v118
	v_rcp_f32_e32 v119, v119
	v_rcp_f32_e32 v108, v108
	v_rcp_f32_e32 v109, v109
	v_pk_mul_f32 v[106:107], v[106:107], v[116:117] op_sel_hi:[1,0]
	v_pk_mul_f32 v[110:111], v[112:113], v[116:117] op_sel_hi:[1,0]
	v_pk_mul_f32 v[106:107], v[106:107], v[118:119]
	v_pk_mul_f32 v[108:109], v[110:111], v[108:109]
	v_cvt_pk_bf16_f32 v106, v106, v107
	v_cvt_pk_bf16_f32 v107, v108, v109
	v_pk_mul_f32 v[108:109], v[98:99], v[0:1] op_sel_hi:[1,0]
	v_pk_mul_f32 v[98:99], v[98:99], v[102:103]
	v_exp_f32_e32 v108, v108
	v_exp_f32_e32 v109, v109
	v_pk_mul_f32 v[98:99], v[98:99], v[116:117] op_sel_hi:[1,0]
	v_pk_add_f32 v[108:109], v[108:109], 1.0 op_sel_hi:[1,0]
	s_nop 0
	v_rcp_f32_e32 v108, v108
	v_rcp_f32_e32 v109, v109
	s_nop 0
	v_pk_mul_f32 v[98:99], v[98:99], v[108:109]
	s_nop 0
	v_cvt_pk_bf16_f32 v108, v98, v99
	v_pk_mul_f32 v[98:99], v[100:101], v[0:1] op_sel_hi:[1,0]
	v_pk_mul_f32 v[100:101], v[104:105], v[116:117] op_sel_hi:[1,0]
	v_exp_f32_e32 v98, v98
	v_exp_f32_e32 v99, v99
	s_nop 0
	v_pk_add_f32 v[98:99], v[98:99], 1.0 op_sel_hi:[1,0]
	s_nop 0
	v_rcp_f32_e32 v98, v98
	v_rcp_f32_e32 v99, v99
	s_nop 0
	v_pk_mul_f32 v[98:99], v[100:101], v[98:99]
	s_nop 0
	v_cvt_pk_bf16_f32 v109, v98, v99
	v_mad_i64_i32 v[98:99], s[2:3], v114, s14, v[132:133]
	global_store_dwordx4 v[98:99], v[106:109], off
	v_or_b32_e32 v98, 32, v134
	v_ashrrev_i32_e32 v99, 31, v98
	v_lshl_add_u64 v[100:101], v[98:99], 2, s[46:47]
	s_waitcnt vmcnt(15)
; __device__ __forceinline__ unsigned pack2(float a, float b) { f32v2_t v = {a, b}; bf16v2_t r = __builtin_convertvector(v, bf16v2_t); return __builtin_bit_cast(unsigned, r); }
; template <int EPI, int N, int K>
; __device__ __forceinline__ void gemm_phase(const KP& p, int l, const bfr* A, const bfr* Bt) {
;     ...
;         for (int m = 0; m < 4; ++m) {
;           int row = erow + ai * HM + wr * 64 + m * 16 + fr;
;           const float r = rs[row];
;           const float nrl = -1.44269504f * r, r2 = r * r;
;           u32x4 pk;
; #pragma unroll
;           for (int bj = 0; bj < 2; ++bj)
; #pragma unroll
;             for (int jj = 0; jj < 2; ++jj) {
;               f32v2_t g2 = {acc[ai][bj][m][0][2 * jj], acc[ai][bj][m][0][2 * jj + 1]};
;               f32v2_t u2 = {acc[ai][bj][m][1][2 * jj], acc[ai][bj][m][1][2 * jj + 1]};
;               f32v2_t t2 = g2 * nrl;
;               f32v2_t e2 = {__builtin_amdgcn_exp2f(t2.x), __builtin_amdgcn_exp2f(t2.y)};
;               f32v2_t d2 = e2 + 1.0f;
;               f32v2_t rc = {__builtin_amdgcn_rcpf(d2.x), __builtin_amdgcn_rcpf(d2.y)};
;               f32v2_t o2 = (g2 * u2) * r2 * rc;
;               pk[bj * 2 + jj] = pack2(o2.x, o2.y);
;             }
;           *(u32x4*)(act + (size_t)row * DFF + (ecol >> 1) + wc * 32 + fq * 8) = pk;
	v_mov_b32_e32 v99, v224
	v_mul_f32_e32 v0, 0xbfb8aa3b, v99
	v_pk_mul_f32 v[102:103], v[90:91], v[0:1] op_sel_hi:[1,0]
	v_pk_mul_f32 v[92:93], v[92:93], v[0:1] op_sel_hi:[1,0]
	v_exp_f32_e32 v102, v102
	v_exp_f32_e32 v103, v103
	v_exp_f32_e32 v92, v92
	v_exp_f32_e32 v93, v93
	v_mul_f32_e32 v100, v99, v99
	v_pk_add_f32 v[102:103], v[102:103], 1.0 op_sel_hi:[1,0]
	v_pk_mul_f32 v[90:91], v[90:91], v[94:95]
	v_pk_add_f32 v[92:93], v[92:93], 1.0 op_sel_hi:[1,0]
	v_rcp_f32_e32 v102, v102
	v_rcp_f32_e32 v103, v103
	v_rcp_f32_e32 v92, v92
	v_rcp_f32_e32 v93, v93
	v_pk_mul_f32 v[90:91], v[90:91], v[100:101] op_sel_hi:[1,0]
	v_pk_mul_f32 v[94:95], v[96:97], v[100:101] op_sel_hi:[1,0]
	v_pk_mul_f32 v[90:91], v[90:91], v[102:103]
	v_pk_mul_f32 v[92:93], v[94:95], v[92:93]
	v_cvt_pk_bf16_f32 v90, v90, v91
	v_cvt_pk_bf16_f32 v91, v92, v93
	v_pk_mul_f32 v[92:93], v[82:83], v[0:1] op_sel_hi:[1,0]
	v_pk_mul_f32 v[82:83], v[82:83], v[86:87]
	v_exp_f32_e32 v92, v92
	v_exp_f32_e32 v93, v93
	v_pk_mul_f32 v[82:83], v[82:83], v[100:101] op_sel_hi:[1,0]
	v_pk_add_f32 v[92:93], v[92:93], 1.0 op_sel_hi:[1,0]
	s_nop 0
	v_rcp_f32_e32 v92, v92
	v_rcp_f32_e32 v93, v93
	s_nop 0
	v_pk_mul_f32 v[82:83], v[82:83], v[92:93]
	s_nop 0
	v_cvt_pk_bf16_f32 v92, v82, v83
	v_pk_mul_f32 v[82:83], v[84:85], v[0:1] op_sel_hi:[1,0]
	v_pk_mul_f32 v[84:85], v[88:89], v[100:101] op_sel_hi:[1,0]
	v_exp_f32_e32 v82, v82
	v_exp_f32_e32 v83, v83
	s_nop 0
	v_pk_add_f32 v[82:83], v[82:83], 1.0 op_sel_hi:[1,0]
	s_nop 0
	v_rcp_f32_e32 v82, v82
	v_rcp_f32_e32 v83, v83
	s_nop 0
	v_pk_mul_f32 v[82:83], v[84:85], v[82:83]
	s_nop 0
	v_cvt_pk_bf16_f32 v93, v82, v83
	v_mad_i64_i32 v[82:83], s[2:3], v98, s14, v[132:133]
	global_store_dwordx4 v[82:83], v[90:93], off
	v_or_b32_e32 v82, 48, v134
	v_ashrrev_i32_e32 v83, 31, v82
	v_lshl_add_u64 v[84:85], v[82:83], 2, s[46:47]
	s_waitcnt vmcnt(15)
	v_mov_b32_e32 v83, v225
	v_mul_f32_e32 v0, 0xbfb8aa3b, v83
	v_pk_mul_f32 v[86:87], v[74:75], v[0:1] op_sel_hi:[1,0]
	v_pk_mul_f32 v[76:77], v[76:77], v[0:1] op_sel_hi:[1,0]
	v_exp_f32_e32 v86, v86
	v_exp_f32_e32 v87, v87
	v_exp_f32_e32 v76, v76
	v_exp_f32_e32 v77, v77
	v_mul_f32_e32 v84, v83, v83
	v_pk_add_f32 v[86:87], v[86:87], 1.0 op_sel_hi:[1,0]
	v_pk_mul_f32 v[74:75], v[74:75], v[78:79]
	v_pk_add_f32 v[76:77], v[76:77], 1.0 op_sel_hi:[1,0]
	v_rcp_f32_e32 v86, v86
	v_rcp_f32_e32 v87, v87
	v_rcp_f32_e32 v76, v76
	v_rcp_f32_e32 v77, v77
	v_pk_mul_f32 v[74:75], v[74:75], v[84:85] op_sel_hi:[1,0]
	v_pk_mul_f32 v[78:79], v[80:81], v[84:85] op_sel_hi:[1,0]
	v_pk_mul_f32 v[74:75], v[74:75], v[86:87]
	v_pk_mul_f32 v[76:77], v[78:79], v[76:77]
	v_cvt_pk_bf16_f32 v74, v74, v75
	v_cvt_pk_bf16_f32 v75, v76, v77
	v_pk_mul_f32 v[76:77], v[66:67], v[0:1] op_sel_hi:[1,0]
	v_pk_mul_f32 v[66:67], v[66:67], v[70:71]
	v_exp_f32_e32 v76, v76
	v_exp_f32_e32 v77, v77
	v_pk_mul_f32 v[66:67], v[66:67], v[84:85] op_sel_hi:[1,0]
	v_pk_add_f32 v[76:77], v[76:77], 1.0 op_sel_hi:[1,0]
	s_nop 0
	v_rcp_f32_e32 v76, v76
	v_rcp_f32_e32 v77, v77
	s_nop 0
	v_pk_mul_f32 v[66:67], v[66:67], v[76:77]
	s_nop 0
	v_cvt_pk_bf16_f32 v76, v66, v67
	v_pk_mul_f32 v[66:67], v[68:69], v[0:1] op_sel_hi:[1,0]
	v_pk_mul_f32 v[68:69], v[72:73], v[84:85] op_sel_hi:[1,0]
	v_exp_f32_e32 v66, v66
	v_exp_f32_e32 v67, v67
	s_nop 0
	v_pk_add_f32 v[66:67], v[66:67], 1.0 op_sel_hi:[1,0]
	s_nop 0
	v_rcp_f32_e32 v66, v66
	v_rcp_f32_e32 v67, v67
	s_nop 0
	v_pk_mul_f32 v[66:67], v[68:69], v[66:67]
	s_nop 0
	v_cvt_pk_bf16_f32 v77, v66, v67
	v_mad_i64_i32 v[66:67], s[2:3], v82, s14, v[132:133]
	global_store_dwordx4 v[66:67], v[74:77], off
	v_add_u32_e32 v66, 0x80, v134
	v_ashrrev_i32_e32 v67, 31, v66
	v_lshl_add_u64 v[68:69], v[66:67], 2, s[46:47]
	s_waitcnt vmcnt(15)
	v_mov_b32_e32 v67, v226
	v_mul_f32_e32 v0, 0xbfb8aa3b, v67
	v_pk_mul_f32 v[70:71], v[58:59], v[0:1] op_sel_hi:[1,0]
	v_pk_mul_f32 v[60:61], v[60:61], v[0:1] op_sel_hi:[1,0]
	v_exp_f32_e32 v70, v70
	v_exp_f32_e32 v71, v71
	v_exp_f32_e32 v60, v60
	v_exp_f32_e32 v61, v61
	v_mul_f32_e32 v68, v67, v67
	v_pk_add_f32 v[70:71], v[70:71], 1.0 op_sel_hi:[1,0]
	v_pk_mul_f32 v[58:59], v[58:59], v[62:63]
	v_pk_add_f32 v[60:61], v[60:61], 1.0 op_sel_hi:[1,0]
	v_rcp_f32_e32 v70, v70
	v_rcp_f32_e32 v71, v71
	v_rcp_f32_e32 v60, v60
	v_rcp_f32_e32 v61, v61
	v_pk_mul_f32 v[58:59], v[58:59], v[68:69] op_sel_hi:[1,0]
	v_pk_mul_f32 v[62:63], v[64:65], v[68:69] op_sel_hi:[1,0]
	v_pk_mul_f32 v[58:59], v[58:59], v[70:71]
	v_pk_mul_f32 v[60:61], v[62:63], v[60:61]
	v_cvt_pk_bf16_f32 v58, v58, v59
	v_cvt_pk_bf16_f32 v59, v60, v61
	v_pk_mul_f32 v[60:61], v[50:51], v[0:1] op_sel_hi:[1,0]
	v_pk_mul_f32 v[50:51], v[50:51], v[54:55]
	v_exp_f32_e32 v60, v60
	v_exp_f32_e32 v61, v61
	v_pk_mul_f32 v[50:51], v[50:51], v[68:69] op_sel_hi:[1,0]
	v_pk_add_f32 v[60:61], v[60:61], 1.0 op_sel_hi:[1,0]
	s_nop 0
	v_rcp_f32_e32 v60, v60
	v_rcp_f32_e32 v61, v61
	s_nop 0
	v_pk_mul_f32 v[50:51], v[50:51], v[60:61]
	s_nop 0
	v_cvt_pk_bf16_f32 v60, v50, v51
	v_pk_mul_f32 v[50:51], v[52:53], v[0:1] op_sel_hi:[1,0]
	v_pk_mul_f32 v[52:53], v[56:57], v[68:69] op_sel_hi:[1,0]
	v_exp_f32_e32 v50, v50
	v_exp_f32_e32 v51, v51
	s_nop 0
	v_pk_add_f32 v[50:51], v[50:51], 1.0 op_sel_hi:[1,0]
	s_nop 0
	v_rcp_f32_e32 v50, v50
	v_rcp_f32_e32 v51, v51
	s_nop 0
	v_pk_mul_f32 v[50:51], v[52:53], v[50:51]
	s_nop 0
	v_cvt_pk_bf16_f32 v61, v50, v51
	v_mad_i64_i32 v[50:51], s[2:3], v66, s14, v[132:133]
	global_store_dwordx4 v[50:51], v[58:61], off
	v_add_u32_e32 v50, 0x90, v134
	v_ashrrev_i32_e32 v51, 31, v50
	v_lshl_add_u64 v[52:53], v[50:51], 2, s[46:47]
	s_waitcnt vmcnt(15)
; __device__ __forceinline__ unsigned pack2(float a, float b) { f32v2_t v = {a, b}; bf16v2_t r = __builtin_convertvector(v, bf16v2_t); return __builtin_bit_cast(unsigned, r); }
; template <int EPI, int N, int K>
; __device__ __forceinline__ void gemm_phase(const KP& p, int l, const bfr* A, const bfr* Bt) {
;     ...
;         for (int m = 0; m < 4; ++m) {
;           int row = erow + ai * HM + wr * 64 + m * 16 + fr;
;           const float r = rs[row];
;           const float nrl = -1.44269504f * r, r2 = r * r;
;           u32x4 pk;
; #pragma unroll
;           for (int bj = 0; bj < 2; ++bj)
; #pragma unroll
;             for (int jj = 0; jj < 2; ++jj) {
;               f32v2_t g2 = {acc[ai][bj][m][0][2 * jj], acc[ai][bj][m][0][2 * jj + 1]};
;               f32v2_t u2 = {acc[ai][bj][m][1][2 * jj], acc[ai][bj][m][1][2 * jj + 1]};
;               f32v2_t t2 = g2 * nrl;
;               f32v2_t e2 = {__builtin_amdgcn_exp2f(t2.x), __builtin_amdgcn_exp2f(t2.y)};
;               f32v2_t d2 = e2 + 1.0f;
;               f32v2_t rc = {__builtin_amdgcn_rcpf(d2.x), __builtin_amdgcn_rcpf(d2.y)};
;               f32v2_t o2 = (g2 * u2) * r2 * rc;
;               pk[bj * 2 + jj] = pack2(o2.x, o2.y);
;             }
;           *(u32x4*)(act + (size_t)row * DFF + (ecol >> 1) + wc * 32 + fq * 8) = pk;
	v_mov_b32_e32 v51, v227
	v_mul_f32_e32 v0, 0xbfb8aa3b, v51
	v_pk_mul_f32 v[54:55], v[42:43], v[0:1] op_sel_hi:[1,0]
	v_pk_mul_f32 v[44:45], v[44:45], v[0:1] op_sel_hi:[1,0]
	v_exp_f32_e32 v54, v54
	v_exp_f32_e32 v55, v55
	v_exp_f32_e32 v44, v44
	v_exp_f32_e32 v45, v45
	v_mul_f32_e32 v52, v51, v51
	v_pk_add_f32 v[54:55], v[54:55], 1.0 op_sel_hi:[1,0]
	v_pk_mul_f32 v[42:43], v[42:43], v[46:47]
	v_pk_add_f32 v[44:45], v[44:45], 1.0 op_sel_hi:[1,0]
	v_rcp_f32_e32 v54, v54
	v_rcp_f32_e32 v55, v55
	v_rcp_f32_e32 v44, v44
	v_rcp_f32_e32 v45, v45
	v_pk_mul_f32 v[42:43], v[42:43], v[52:53] op_sel_hi:[1,0]
	v_pk_mul_f32 v[46:47], v[48:49], v[52:53] op_sel_hi:[1,0]
	v_pk_mul_f32 v[42:43], v[42:43], v[54:55]
	v_pk_mul_f32 v[44:45], v[46:47], v[44:45]
	v_cvt_pk_bf16_f32 v42, v42, v43
	v_cvt_pk_bf16_f32 v43, v44, v45
	v_pk_mul_f32 v[44:45], v[34:35], v[0:1] op_sel_hi:[1,0]
	v_pk_mul_f32 v[34:35], v[34:35], v[38:39]
	v_exp_f32_e32 v44, v44
	v_exp_f32_e32 v45, v45
	v_pk_mul_f32 v[34:35], v[34:35], v[52:53] op_sel_hi:[1,0]
	v_pk_add_f32 v[44:45], v[44:45], 1.0 op_sel_hi:[1,0]
	s_nop 0
	v_rcp_f32_e32 v44, v44
	v_rcp_f32_e32 v45, v45
	s_nop 0
	v_pk_mul_f32 v[34:35], v[34:35], v[44:45]
	s_nop 0
	v_cvt_pk_bf16_f32 v44, v34, v35
	v_pk_mul_f32 v[34:35], v[36:37], v[0:1] op_sel_hi:[1,0]
	v_pk_mul_f32 v[36:37], v[40:41], v[52:53] op_sel_hi:[1,0]
	v_exp_f32_e32 v34, v34
	v_exp_f32_e32 v35, v35
	s_nop 0
	v_pk_add_f32 v[34:35], v[34:35], 1.0 op_sel_hi:[1,0]
	s_nop 0
	v_rcp_f32_e32 v34, v34
	v_rcp_f32_e32 v35, v35
	s_nop 0
	v_pk_mul_f32 v[34:35], v[36:37], v[34:35]
	s_nop 0
	v_cvt_pk_bf16_f32 v45, v34, v35
	v_mad_i64_i32 v[34:35], s[2:3], v50, s14, v[132:133]
	global_store_dwordx4 v[34:35], v[42:45], off
	v_add_u32_e32 v34, 0xa0, v134
	v_ashrrev_i32_e32 v35, 31, v34
	v_lshl_add_u64 v[36:37], v[34:35], 2, s[46:47]
	s_waitcnt vmcnt(15)
	v_mov_b32_e32 v35, v228
	v_mul_f32_e32 v0, 0xbfb8aa3b, v35
	v_pk_mul_f32 v[38:39], v[26:27], v[0:1] op_sel_hi:[1,0]
	v_pk_mul_f32 v[28:29], v[28:29], v[0:1] op_sel_hi:[1,0]
	v_exp_f32_e32 v38, v38
	v_exp_f32_e32 v39, v39
	v_exp_f32_e32 v28, v28
	v_exp_f32_e32 v29, v29
	v_mul_f32_e32 v36, v35, v35
	v_pk_add_f32 v[38:39], v[38:39], 1.0 op_sel_hi:[1,0]
	v_pk_mul_f32 v[26:27], v[26:27], v[30:31]
	v_pk_add_f32 v[28:29], v[28:29], 1.0 op_sel_hi:[1,0]
	v_rcp_f32_e32 v38, v38
	v_rcp_f32_e32 v39, v39
	v_rcp_f32_e32 v28, v28
	v_rcp_f32_e32 v29, v29
	v_pk_mul_f32 v[26:27], v[26:27], v[36:37] op_sel_hi:[1,0]
	v_pk_mul_f32 v[30:31], v[32:33], v[36:37] op_sel_hi:[1,0]
	v_pk_mul_f32 v[26:27], v[26:27], v[38:39]
	v_pk_mul_f32 v[28:29], v[30:31], v[28:29]
	v_cvt_pk_bf16_f32 v26, v26, v27
	v_cvt_pk_bf16_f32 v27, v28, v29
	v_pk_mul_f32 v[28:29], v[18:19], v[0:1] op_sel_hi:[1,0]
	v_pk_mul_f32 v[18:19], v[18:19], v[22:23]
	v_exp_f32_e32 v28, v28
	v_exp_f32_e32 v29, v29
	v_pk_mul_f32 v[18:19], v[18:19], v[36:37] op_sel_hi:[1,0]
	v_pk_add_f32 v[28:29], v[28:29], 1.0 op_sel_hi:[1,0]
	s_nop 0
	v_rcp_f32_e32 v28, v28
	v_rcp_f32_e32 v29, v29
	s_nop 0
	v_pk_mul_f32 v[18:19], v[18:19], v[28:29]
	s_nop 0
	v_cvt_pk_bf16_f32 v28, v18, v19
	v_pk_mul_f32 v[18:19], v[20:21], v[0:1] op_sel_hi:[1,0]
	v_pk_mul_f32 v[20:21], v[24:25], v[36:37] op_sel_hi:[1,0]
	v_exp_f32_e32 v18, v18
	v_exp_f32_e32 v19, v19
	s_nop 0
	v_pk_add_f32 v[18:19], v[18:19], 1.0 op_sel_hi:[1,0]
	s_nop 0
	v_rcp_f32_e32 v18, v18
	v_rcp_f32_e32 v19, v19
	s_nop 0
	v_pk_mul_f32 v[18:19], v[20:21], v[18:19]
	s_nop 0
	v_cvt_pk_bf16_f32 v29, v18, v19
	v_mad_i64_i32 v[18:19], s[2:3], v34, s14, v[132:133]
	global_store_dwordx4 v[18:19], v[26:29], off
	v_add_u32_e32 v18, 0xb0, v134
	v_ashrrev_i32_e32 v19, 31, v18
	v_lshl_add_u64 v[20:21], v[18:19], 2, s[46:47]
	s_waitcnt vmcnt(15)
	v_mov_b32_e32 v19, v229
	v_mul_f32_e32 v0, 0xbfb8aa3b, v19
	v_pk_mul_f32 v[22:23], v[10:11], v[0:1] op_sel_hi:[1,0]
	v_pk_mul_f32 v[12:13], v[12:13], v[0:1] op_sel_hi:[1,0]
	v_exp_f32_e32 v22, v22
	v_exp_f32_e32 v23, v23
	v_exp_f32_e32 v12, v12
	v_exp_f32_e32 v13, v13
	v_mul_f32_e32 v20, v19, v19
	v_pk_add_f32 v[22:23], v[22:23], 1.0 op_sel_hi:[1,0]
	v_pk_mul_f32 v[10:11], v[10:11], v[14:15]
	v_pk_add_f32 v[12:13], v[12:13], 1.0 op_sel_hi:[1,0]
	v_rcp_f32_e32 v22, v22
	v_rcp_f32_e32 v23, v23
	v_rcp_f32_e32 v12, v12
	v_rcp_f32_e32 v13, v13
	v_pk_mul_f32 v[10:11], v[10:11], v[20:21] op_sel_hi:[1,0]
	v_pk_mul_f32 v[14:15], v[16:17], v[20:21] op_sel_hi:[1,0]
	v_pk_mul_f32 v[10:11], v[10:11], v[22:23]
	v_pk_mul_f32 v[12:13], v[14:15], v[12:13]
	v_cvt_pk_bf16_f32 v10, v10, v11
	v_cvt_pk_bf16_f32 v11, v12, v13
	v_pk_mul_f32 v[12:13], v[2:3], v[0:1] op_sel_hi:[1,0]
	v_pk_mul_f32 v[2:3], v[2:3], v[6:7]
	v_exp_f32_e32 v12, v12
	v_exp_f32_e32 v13, v13
	v_pk_mul_f32 v[2:3], v[2:3], v[20:21] op_sel_hi:[1,0]
	v_pk_add_f32 v[12:13], v[12:13], 1.0 op_sel_hi:[1,0]
	s_nop 0
	v_rcp_f32_e32 v12, v12
	v_rcp_f32_e32 v13, v13
	s_nop 0
	v_pk_mul_f32 v[2:3], v[2:3], v[12:13]
	s_nop 0
	v_cvt_pk_bf16_f32 v12, v2, v3
	v_pk_mul_f32 v[2:3], v[4:5], v[0:1] op_sel_hi:[1,0]
	v_pk_mul_f32 v[4:5], v[8:9], v[20:21] op_sel_hi:[1,0]
	v_exp_f32_e32 v2, v2
	v_exp_f32_e32 v3, v3
	s_nop 0
	v_pk_add_f32 v[2:3], v[2:3], 1.0 op_sel_hi:[1,0]
	s_nop 0
	v_rcp_f32_e32 v2, v2
	v_rcp_f32_e32 v3, v3
	s_nop 0
	v_pk_mul_f32 v[2:3], v[4:5], v[2:3]
	s_nop 0
	v_cvt_pk_bf16_f32 v13, v2, v3
	v_mad_i64_i32 v[2:3], s[2:3], v18, s14, v[132:133]
	global_store_dwordx4 v[2:3], v[10:13], off
	s_cbranch_vccnz .LBB0_293

; #define STAGE_A(P, BASE, br, kt) STAGE_B(P, BASE, br, kt)
; template <int EPI, int N, int K>
; __device__ __forceinline__ void gemm_phase(const KP& p, int l, const bfr* A, const bfr* Bt) {
;     ...
;     if (Lt + p.nblk < nwg) {
;       TILE_COORDS(Lt + p.nblk, brow, bcol, pn);
;       STAGE_B(SB(0, 0), Bt, bcol, 0); STAGE_A(SA(0, 0), A, brow, 0);
;       STAGE_B(SB(0, 1), Bt, bcol + HALF, 0); STAGE_A(SA(0, 1), A, brow + HM, 0);
;     }
;     const float* rs = (const float*)(p.ws + OFF_RS);
;     if (EPI == 1) {
;       bfr* act = (bfr*)(p.ws + OFF_U);
; #pragma unroll
;       for (int ai = 0; ai < 2; ++ai)
; #pragma unroll
;         for (int m = 0; m < 4; ++m) {
;           int row = erow + ai * HM + wr * 64 + m * 16 + fr;
;           const float r = rs[row];
.LBB0_242:
	s_or_b64 exec, exec, s[50:51]
	v_add_u32_e32 v230, s76, v147
	v_ashrrev_i32_e32 v231, 31, v230
	v_lshl_add_u64 v[230:231], v[230:231], 2, s[46:47]
	global_load_dword v222, v[230:231], off
	global_load_dword v223, v[230:231], off offset:64
	global_load_dword v224, v[230:231], off offset:128
	global_load_dword v225, v[230:231], off offset:192
	global_load_dword v226, v[230:231], off offset:512
	global_load_dword v227, v[230:231], off offset:576
	global_load_dword v228, v[230:231], off offset:640
	global_load_dword v229, v[230:231], off offset:704
	s_add_i32 s82, s82, s18
	s_cmpk_gt_i32 s82, 0xb57
	s_cselect_b64 s[50:51], -1, 0
	s_and_b64 vcc, exec, s[50:51]
	s_mov_b32 s52, s78
	s_mov_b32 s74, s76
	s_cbranch_vccnz .Lepi1a_nonext
	s_ashr_i32 s2, s82, 31
	s_lshr_b32 s2, s2, 29
	s_add_i32 s2, s82, s2
	s_ashr_i32 s3, s2, 3
	s_and_b32 s2, s2, -8
	s_sub_i32 s2, s82, s2
	s_cmp_lt_i32 s2, 0
	s_movk_i32 s14, 0x16c
	s_cselect_b32 s14, s14, 0x16b
	s_mul_i32 s2, s14, s2
	s_add_i32 s2, s2, s3
	s_mul_hi_i32 s3, s2, 0x2e8ba2e9
	s_lshr_b32 s14, s3, 31
	s_ashr_i32 s3, s3, 5
	s_add_i32 s3, s3, s14
	s_lshl_b32 s14, s3, 3
	s_sub_i32 s15, 0x84, s14
	s_min_u32 s15, s15, 8
	s_mulk_i32 s3, 0xb0
	s_sub_i32 s52, s2, s3
	v_cvt_f32_ubyte0_e32 v132, s15
	v_cvt_f32_i32_e32 v0, s52
	v_rcp_iflag_f32_e32 v133, v132
	s_ashr_i32 s2, s52, 30
	s_or_b32 s53, s2, 1
	v_readlane_b32 s16, v255, 45
	v_mul_f32_e32 v133, v0, v133
	v_trunc_f32_e32 v133, v133
	v_fma_f32 v0, -v133, v132, v0
	v_cvt_i32_f32_e32 v133, v133
	v_cmp_ge_f32_e64 s[2:3], |v0|, v132
	s_and_b64 s[2:3], s[2:3], exec
	s_cselect_b32 s2, s53, 0
	v_readfirstlane_b32 s3, v133
	s_add_i32 s2, s3, s2
	s_sext_i32_i16 s3, s2
	s_mul_i32 s2, s2, s15
	s_sub_i32 s2, s52, s2
	s_sext_i32_i16 s2, s2
	s_lshl_b32 s52, s3, 8
	s_add_i32 s14, s14, s2
	s_ashr_i32 s53, s52, 31
	s_lshl_b32 s74, s14, 8
	s_lshl_b64 s[2:3], s[52:53], 11
	s_add_u32 s2, s33, s2
	v_readfirstlane_b32 s14, v139
	s_addc_u32 s3, s72, s3
	v_mov_b32_e32 v0, v137
	v_mov_b32_e32 v132, v138
	s_mov_b32 m0, s14
	v_readfirstlane_b32 s14, v140
	s_ashr_i32 s75, s74, 31
	global_load_lds_dwordx4 v0, s[2:3]
	s_mov_b32 m0, s14
	v_readlane_b32 s17, v255, 46
	global_load_lds_dwordx4 v132, s[2:3]
	s_lshl_b64 s[2:3], s[74:75], 11
	s_add_u32 s2, s16, s2
	v_readfirstlane_b32 s14, v141
	s_addc_u32 s3, s17, s3
	v_mov_b32_e32 v0, v138
	v_mov_b32_e32 v132, v137
	s_mov_b32 m0, s14
	v_readfirstlane_b32 s14, v142
	s_nop 0
	global_load_lds_dwordx4 v132, s[2:3]
	s_mov_b32 m0, s14
	v_readfirstlane_b32 s14, v143
	global_load_lds_dwordx4 v0, s[2:3]
	s_or_b32 s2, s52, 0x80
	s_ashr_i32 s3, s2, 31
	s_lshl_b64 s[2:3], s[2:3], 11
	s_add_u32 s2, s33, s2
	s_addc_u32 s3, s72, s3
	v_mov_b32_e32 v0, v138
	v_mov_b32_e32 v132, v137
	s_mov_b32 m0, s14
	v_readfirstlane_b32 s14, v144
	s_nop 0
	global_load_lds_dwordx4 v132, s[2:3]
	s_mov_b32 m0, s14
	v_readfirstlane_b32 s14, v145
	global_load_lds_dwordx4 v0, s[2:3]
	s_or_b32 s2, s74, 0x80
	s_ashr_i32 s3, s2, 31
	s_lshl_b64 s[2:3], s[2:3], 11
	s_add_u32 s2, s16, s2
	s_addc_u32 s3, s17, s3
	v_mov_b32_e32 v0, v137
	v_mov_b32_e32 v132, v138
	s_mov_b32 m0, s14
	v_readfirstlane_b32 s14, v146
	s_nop 0
	global_load_lds_dwordx4 v0, s[2:3]
	s_mov_b32 m0, s14
	s_nop 0
	global_load_lds_dwordx4 v132, s[2:3]
	s_branch .LBB0_235
.Lepi1a_nonext:
	global_load_dword v232, v[230:231], off
	global_load_dword v232, v[230:231], off
	global_load_dword v232, v[230:231], off
	global_load_dword v232, v[230:231], off
	global_load_dword v232, v[230:231], off
	global_load_dword v232, v[230:231], off
	global_load_dword v232, v[230:231], off
	global_load_dword v232, v[230:231], off
	s_branch .LBB0_235

; __device__ __forceinline__ unsigned pack2(float a, float b) { f32v2_t v = {a, b}; bf16v2_t r = __builtin_convertvector(v, bf16v2_t); return __builtin_bit_cast(unsigned, r); }
; template <int EPI, int N, int K>
; __device__ __forceinline__ void gemm_phase(const KP& p, int l, const bfr* A, const bfr* Bt) {
;     ...
;     if (EPI == 1) {
;       bfr* act = (bfr*)(p.ws + OFF_U);
; #pragma unroll
;       for (int ai = 0; ai < 2; ++ai)
; #pragma unroll
;         for (int m = 0; m < 4; ++m) {
;           int row = erow + ai * HM + wr * 64 + m * 16 + fr;
;           const float r = rs[row];
;           const float nrl = -1.44269504f * r, r2 = r * r;
;           u32x4 pk;
; #pragma unroll
;           for (int bj = 0; bj < 2; ++bj)
; #pragma unroll
;             for (int jj = 0; jj < 2; ++jj) {
;               f32v2_t g2 = {acc[ai][bj][m][0][2 * jj], acc[ai][bj][m][0][2 * jj + 1]};
;               f32v2_t u2 = {acc[ai][bj][m][1][2 * jj], acc[ai][bj][m][1][2 * jj + 1]};
;               f32v2_t t2 = g2 * nrl;
;               f32v2_t e2 = {__builtin_amdgcn_exp2f(t2.x), __builtin_amdgcn_exp2f(t2.y)};
;               f32v2_t d2 = e2 + 1.0f;
;               f32v2_t rc = {__builtin_amdgcn_rcpf(d2.x), __builtin_amdgcn_rcpf(d2.y)};
;               f32v2_t o2 = (g2 * u2) * r2 * rc;
;               pk[bj * 2 + jj] = pack2(o2.x, o2.y);
;             }
;           *(u32x4*)(act + (size_t)row * DFF + (ecol >> 1) + wc * 32 + fq * 8) = pk;
;         }
.LBB0_1141:
	v_add_u32_e32 v134, s46, v147
	v_ashrrev_i32_e32 v135, 31, v134
	v_lshl_add_u64 v[166:167], v[134:135], 2, s[0:1]
	v_pk_mul_f32 v[128:129], v[124:125], v[128:129]
	s_ashr_i32 s2, s50, 1
	v_pk_mul_f32 v[120:121], v[116:117], v[120:121]
	s_ashr_i32 s3, s2, 31
	v_lshl_add_u64 v[132:133], s[2:3], 1, v[130:131]
	s_movk_i32 s14, 0x1600
	v_pk_mul_f32 v[112:113], v[108:109], v[112:113]
	v_pk_mul_f32 v[104:105], v[100:101], v[104:105]
	v_pk_mul_f32 v[96:97], v[92:93], v[96:97]
	v_pk_mul_f32 v[88:89], v[84:85], v[88:89]
	v_pk_mul_f32 v[80:81], v[76:77], v[80:81]
	v_pk_mul_f32 v[72:73], v[68:69], v[72:73]
	v_pk_mul_f32 v[64:65], v[60:61], v[64:65]
	v_pk_mul_f32 v[56:57], v[52:53], v[56:57]
	v_pk_mul_f32 v[48:49], v[44:45], v[48:49]
	v_pk_mul_f32 v[40:41], v[36:37], v[40:41]
	v_pk_mul_f32 v[32:33], v[28:29], v[32:33]
	v_pk_mul_f32 v[24:25], v[20:21], v[24:25]
	v_pk_mul_f32 v[16:17], v[12:13], v[16:17]
	v_pk_mul_f32 v[8:9], v[4:5], v[8:9]
	s_andn2_b64 vcc, exec, s[42:43]
	s_mov_b32 s46, s44
	s_mov_b32 s50, s36
	s_waitcnt vmcnt(15)
	v_mov_b32_e32 v135, v222
	v_mul_f32_e32 v0, 0xbfb8aa3b, v135
	v_pk_mul_f32 v[168:169], v[122:123], v[0:1] op_sel_hi:[1,0]
	v_pk_mul_f32 v[124:125], v[124:125], v[0:1] op_sel_hi:[1,0]
	v_exp_f32_e32 v168, v168
	v_exp_f32_e32 v169, v169
	v_exp_f32_e32 v124, v124
	v_exp_f32_e32 v125, v125
	v_mul_f32_e32 v166, v135, v135
	v_pk_add_f32 v[168:169], v[168:169], 1.0 op_sel_hi:[1,0]
	v_pk_mul_f32 v[122:123], v[122:123], v[126:127]
	v_pk_add_f32 v[124:125], v[124:125], 1.0 op_sel_hi:[1,0]
	v_rcp_f32_e32 v168, v168
	v_rcp_f32_e32 v169, v169
	v_rcp_f32_e32 v124, v124
	v_rcp_f32_e32 v125, v125
	v_pk_mul_f32 v[122:123], v[122:123], v[166:167] op_sel_hi:[1,0]
	v_pk_mul_f32 v[126:127], v[128:129], v[166:167] op_sel_hi:[1,0]
	v_pk_mul_f32 v[122:123], v[122:123], v[168:169]
	v_pk_mul_f32 v[124:125], v[126:127], v[124:125]
	v_cvt_pk_bf16_f32 v122, v122, v123
	v_cvt_pk_bf16_f32 v123, v124, v125
	v_pk_mul_f32 v[124:125], v[114:115], v[0:1] op_sel_hi:[1,0]
	v_pk_mul_f32 v[114:115], v[114:115], v[118:119]
	v_exp_f32_e32 v124, v124
	v_exp_f32_e32 v125, v125
	v_pk_mul_f32 v[114:115], v[114:115], v[166:167] op_sel_hi:[1,0]
	v_pk_add_f32 v[124:125], v[124:125], 1.0 op_sel_hi:[1,0]
	s_nop 0
	v_rcp_f32_e32 v124, v124
	v_rcp_f32_e32 v125, v125
	s_nop 0
	v_pk_mul_f32 v[114:115], v[114:115], v[124:125]
	s_nop 0
	v_cvt_pk_bf16_f32 v124, v114, v115
	v_pk_mul_f32 v[114:115], v[116:117], v[0:1] op_sel_hi:[1,0]
	v_pk_mul_f32 v[116:117], v[120:121], v[166:167] op_sel_hi:[1,0]
	v_exp_f32_e32 v114, v114
	v_exp_f32_e32 v115, v115
	s_nop 0
	v_pk_add_f32 v[114:115], v[114:115], 1.0 op_sel_hi:[1,0]
	s_nop 0
	v_rcp_f32_e32 v114, v114
	v_rcp_f32_e32 v115, v115
	s_nop 0
	v_pk_mul_f32 v[114:115], v[116:117], v[114:115]
	s_nop 0
	v_cvt_pk_bf16_f32 v125, v114, v115
	v_mad_i64_i32 v[114:115], s[2:3], v134, s14, v[132:133]
	global_store_dwordx4 v[114:115], v[122:125], off
	v_or_b32_e32 v114, 16, v134
	v_ashrrev_i32_e32 v115, 31, v114
	v_lshl_add_u64 v[116:117], v[114:115], 2, s[0:1]
	s_waitcnt vmcnt(15)
	v_mov_b32_e32 v115, v223
	v_mul_f32_e32 v0, 0xbfb8aa3b, v115
	v_pk_mul_f32 v[118:119], v[106:107], v[0:1] op_sel_hi:[1,0]
	v_pk_mul_f32 v[108:109], v[108:109], v[0:1] op_sel_hi:[1,0]
	v_exp_f32_e32 v118, v118
	v_exp_f32_e32 v119, v119
	v_exp_f32_e32 v108, v108
	v_exp_f32_e32 v109, v109
	v_mul_f32_e32 v116, v115, v115
	v_pk_add_f32 v[118:119], v[118:119], 1.0 op_sel_hi:[1,0]
	v_pk_mul_f32 v[106:107], v[106:107], v[110:111]
	v_pk_add_f32 v[108:109], v[108:109], 1.0 op_sel_hi:[1,0]
	v_rcp_f32_e32 v118, v118
	v_rcp_f32_e32 v119, v119
	v_rcp_f32_e32 v108, v108
	v_rcp_f32_e32 v109, v109
	v_pk_mul_f32 v[106:107], v[106:107], v[116:117] op_sel_hi:[1,0]
	v_pk_mul_f32 v[110:111], v[112:113], v[116:117] op_sel_hi:[1,0]
	v_pk_mul_f32 v[106:107], v[106:107], v[118:119]
	v_pk_mul_f32 v[108:109], v[110:111], v[108:109]
	v_cvt_pk_bf16_f32 v106, v106, v107
	v_cvt_pk_bf16_f32 v107, v108, v109
	v_pk_mul_f32 v[108:109], v[98:99], v[0:1] op_sel_hi:[1,0]
	v_pk_mul_f32 v[98:99], v[98:99], v[102:103]
	v_exp_f32_e32 v108, v108
	v_exp_f32_e32 v109, v109
	v_pk_mul_f32 v[98:99], v[98:99], v[116:117] op_sel_hi:[1,0]
	v_pk_add_f32 v[108:109], v[108:109], 1.0 op_sel_hi:[1,0]
	s_nop 0
	v_rcp_f32_e32 v108, v108
	v_rcp_f32_e32 v109, v109
	s_nop 0
	v_pk_mul_f32 v[98:99], v[98:99], v[108:109]
	s_nop 0
	v_cvt_pk_bf16_f32 v108, v98, v99
	v_pk_mul_f32 v[98:99], v[100:101], v[0:1] op_sel_hi:[1,0]
	v_pk_mul_f32 v[100:101], v[104:105], v[116:117] op_sel_hi:[1,0]
	v_exp_f32_e32 v98, v98
	v_exp_f32_e32 v99, v99
	s_nop 0
	v_pk_add_f32 v[98:99], v[98:99], 1.0 op_sel_hi:[1,0]
	s_nop 0
	v_rcp_f32_e32 v98, v98
	v_rcp_f32_e32 v99, v99
	s_nop 0
	v_pk_mul_f32 v[98:99], v[100:101], v[98:99]
	s_nop 0
	v_cvt_pk_bf16_f32 v109, v98, v99
	v_mad_i64_i32 v[98:99], s[2:3], v114, s14, v[132:133]
	global_store_dwordx4 v[98:99], v[106:109], off
	v_or_b32_e32 v98, 32, v134
	v_ashrrev_i32_e32 v99, 31, v98
	v_lshl_add_u64 v[100:101], v[98:99], 2, s[0:1]
	s_waitcnt vmcnt(15)
; __device__ __forceinline__ unsigned pack2(float a, float b) { f32v2_t v = {a, b}; bf16v2_t r = __builtin_convertvector(v, bf16v2_t); return __builtin_bit_cast(unsigned, r); }
; template <int EPI, int N, int K>
; __device__ __forceinline__ void gemm_phase(const KP& p, int l, const bfr* A, const bfr* Bt) {
;     ...
;     if (EPI == 1) {
;       bfr* act = (bfr*)(p.ws + OFF_U);
; #pragma unroll
;       for (int ai = 0; ai < 2; ++ai)
; #pragma unroll
;         for (int m = 0; m < 4; ++m) {
;           int row = erow + ai * HM + wr * 64 + m * 16 + fr;
;           const float r = rs[row];
;           const float nrl = -1.44269504f * r, r2 = r * r;
;           u32x4 pk;
; #pragma unroll
;           for (int bj = 0; bj < 2; ++bj)
; #pragma unroll
;             for (int jj = 0; jj < 2; ++jj) {
;               f32v2_t g2 = {acc[ai][bj][m][0][2 * jj], acc[ai][bj][m][0][2 * jj + 1]};
;               f32v2_t u2 = {acc[ai][bj][m][1][2 * jj], acc[ai][bj][m][1][2 * jj + 1]};
;               f32v2_t t2 = g2 * nrl;
;               f32v2_t e2 = {__builtin_amdgcn_exp2f(t2.x), __builtin_amdgcn_exp2f(t2.y)};
;               f32v2_t d2 = e2 + 1.0f;
;               f32v2_t rc = {__builtin_amdgcn_rcpf(d2.x), __builtin_amdgcn_rcpf(d2.y)};
;               f32v2_t o2 = (g2 * u2) * r2 * rc;
;               pk[bj * 2 + jj] = pack2(o2.x, o2.y);
;             }
;           *(u32x4*)(act + (size_t)row * DFF + (ecol >> 1) + wc * 32 + fq * 8) = pk;
;         }
	v_mov_b32_e32 v99, v224
	v_mul_f32_e32 v0, 0xbfb8aa3b, v99
	v_pk_mul_f32 v[102:103], v[90:91], v[0:1] op_sel_hi:[1,0]
	v_pk_mul_f32 v[92:93], v[92:93], v[0:1] op_sel_hi:[1,0]
	v_exp_f32_e32 v102, v102
	v_exp_f32_e32 v103, v103
	v_exp_f32_e32 v92, v92
	v_exp_f32_e32 v93, v93
	v_mul_f32_e32 v100, v99, v99
	v_pk_add_f32 v[102:103], v[102:103], 1.0 op_sel_hi:[1,0]
	v_pk_mul_f32 v[90:91], v[90:91], v[94:95]
	v_pk_add_f32 v[92:93], v[92:93], 1.0 op_sel_hi:[1,0]
	v_rcp_f32_e32 v102, v102
	v_rcp_f32_e32 v103, v103
	v_rcp_f32_e32 v92, v92
	v_rcp_f32_e32 v93, v93
	v_pk_mul_f32 v[90:91], v[90:91], v[100:101] op_sel_hi:[1,0]
	v_pk_mul_f32 v[94:95], v[96:97], v[100:101] op_sel_hi:[1,0]
	v_pk_mul_f32 v[90:91], v[90:91], v[102:103]
	v_pk_mul_f32 v[92:93], v[94:95], v[92:93]
	v_cvt_pk_bf16_f32 v90, v90, v91
	v_cvt_pk_bf16_f32 v91, v92, v93
	v_pk_mul_f32 v[92:93], v[82:83], v[0:1] op_sel_hi:[1,0]
	v_pk_mul_f32 v[82:83], v[82:83], v[86:87]
	v_exp_f32_e32 v92, v92
	v_exp_f32_e32 v93, v93
	v_pk_mul_f32 v[82:83], v[82:83], v[100:101] op_sel_hi:[1,0]
	v_pk_add_f32 v[92:93], v[92:93], 1.0 op_sel_hi:[1,0]
	s_nop 0
	v_rcp_f32_e32 v92, v92
	v_rcp_f32_e32 v93, v93
	s_nop 0
	v_pk_mul_f32 v[82:83], v[82:83], v[92:93]
	s_nop 0
	v_cvt_pk_bf16_f32 v92, v82, v83
	v_pk_mul_f32 v[82:83], v[84:85], v[0:1] op_sel_hi:[1,0]
	v_pk_mul_f32 v[84:85], v[88:89], v[100:101] op_sel_hi:[1,0]
	v_exp_f32_e32 v82, v82
	v_exp_f32_e32 v83, v83
	s_nop 0
	v_pk_add_f32 v[82:83], v[82:83], 1.0 op_sel_hi:[1,0]
	s_nop 0
	v_rcp_f32_e32 v82, v82
	v_rcp_f32_e32 v83, v83
	s_nop 0
	v_pk_mul_f32 v[82:83], v[84:85], v[82:83]
	s_nop 0
	v_cvt_pk_bf16_f32 v93, v82, v83
	v_mad_i64_i32 v[82:83], s[2:3], v98, s14, v[132:133]
	global_store_dwordx4 v[82:83], v[90:93], off
	v_or_b32_e32 v82, 48, v134
	v_ashrrev_i32_e32 v83, 31, v82
	v_lshl_add_u64 v[84:85], v[82:83], 2, s[0:1]
	s_waitcnt vmcnt(15)
	v_mov_b32_e32 v83, v225
	v_mul_f32_e32 v0, 0xbfb8aa3b, v83
	v_pk_mul_f32 v[86:87], v[74:75], v[0:1] op_sel_hi:[1,0]
	v_pk_mul_f32 v[76:77], v[76:77], v[0:1] op_sel_hi:[1,0]
	v_exp_f32_e32 v86, v86
	v_exp_f32_e32 v87, v87
	v_exp_f32_e32 v76, v76
	v_exp_f32_e32 v77, v77
	v_mul_f32_e32 v84, v83, v83
	v_pk_add_f32 v[86:87], v[86:87], 1.0 op_sel_hi:[1,0]
	v_pk_mul_f32 v[74:75], v[74:75], v[78:79]
	v_pk_add_f32 v[76:77], v[76:77], 1.0 op_sel_hi:[1,0]
	v_rcp_f32_e32 v86, v86
	v_rcp_f32_e32 v87, v87
	v_rcp_f32_e32 v76, v76
	v_rcp_f32_e32 v77, v77
	v_pk_mul_f32 v[74:75], v[74:75], v[84:85] op_sel_hi:[1,0]
	v_pk_mul_f32 v[78:79], v[80:81], v[84:85] op_sel_hi:[1,0]
	v_pk_mul_f32 v[74:75], v[74:75], v[86:87]
	v_pk_mul_f32 v[76:77], v[78:79], v[76:77]
	v_cvt_pk_bf16_f32 v74, v74, v75
	v_cvt_pk_bf16_f32 v75, v76, v77
	v_pk_mul_f32 v[76:77], v[66:67], v[0:1] op_sel_hi:[1,0]
	v_pk_mul_f32 v[66:67], v[66:67], v[70:71]
	v_exp_f32_e32 v76, v76
	v_exp_f32_e32 v77, v77
	v_pk_mul_f32 v[66:67], v[66:67], v[84:85] op_sel_hi:[1,0]
	v_pk_add_f32 v[76:77], v[76:77], 1.0 op_sel_hi:[1,0]
	s_nop 0
	v_rcp_f32_e32 v76, v76
	v_rcp_f32_e32 v77, v77
	s_nop 0
	v_pk_mul_f32 v[66:67], v[66:67], v[76:77]
	s_nop 0
	v_cvt_pk_bf16_f32 v76, v66, v67
	v_pk_mul_f32 v[66:67], v[68:69], v[0:1] op_sel_hi:[1,0]
	v_pk_mul_f32 v[68:69], v[72:73], v[84:85] op_sel_hi:[1,0]
	v_exp_f32_e32 v66, v66
	v_exp_f32_e32 v67, v67
	s_nop 0
	v_pk_add_f32 v[66:67], v[66:67], 1.0 op_sel_hi:[1,0]
	s_nop 0
	v_rcp_f32_e32 v66, v66
	v_rcp_f32_e32 v67, v67
	s_nop 0
	v_pk_mul_f32 v[66:67], v[68:69], v[66:67]
	s_nop 0
	v_cvt_pk_bf16_f32 v77, v66, v67
	v_mad_i64_i32 v[66:67], s[2:3], v82, s14, v[132:133]
	global_store_dwordx4 v[66:67], v[74:77], off
	v_add_u32_e32 v66, 0x80, v134
	v_ashrrev_i32_e32 v67, 31, v66
	v_lshl_add_u64 v[68:69], v[66:67], 2, s[0:1]
	s_waitcnt vmcnt(15)
	v_mov_b32_e32 v67, v226
	v_mul_f32_e32 v0, 0xbfb8aa3b, v67
	v_pk_mul_f32 v[70:71], v[58:59], v[0:1] op_sel_hi:[1,0]
	v_pk_mul_f32 v[60:61], v[60:61], v[0:1] op_sel_hi:[1,0]
	v_exp_f32_e32 v70, v70
	v_exp_f32_e32 v71, v71
	v_exp_f32_e32 v60, v60
	v_exp_f32_e32 v61, v61
	v_mul_f32_e32 v68, v67, v67
	v_pk_add_f32 v[70:71], v[70:71], 1.0 op_sel_hi:[1,0]
	v_pk_mul_f32 v[58:59], v[58:59], v[62:63]
	v_pk_add_f32 v[60:61], v[60:61], 1.0 op_sel_hi:[1,0]
	v_rcp_f32_e32 v70, v70
	v_rcp_f32_e32 v71, v71
	v_rcp_f32_e32 v60, v60
	v_rcp_f32_e32 v61, v61
	v_pk_mul_f32 v[58:59], v[58:59], v[68:69] op_sel_hi:[1,0]
	v_pk_mul_f32 v[62:63], v[64:65], v[68:69] op_sel_hi:[1,0]
	v_pk_mul_f32 v[58:59], v[58:59], v[70:71]
	v_pk_mul_f32 v[60:61], v[62:63], v[60:61]
	v_cvt_pk_bf16_f32 v58, v58, v59
	v_cvt_pk_bf16_f32 v59, v60, v61
	v_pk_mul_f32 v[60:61], v[50:51], v[0:1] op_sel_hi:[1,0]
	v_pk_mul_f32 v[50:51], v[50:51], v[54:55]
	v_exp_f32_e32 v60, v60
	v_exp_f32_e32 v61, v61
	v_pk_mul_f32 v[50:51], v[50:51], v[68:69] op_sel_hi:[1,0]
	v_pk_add_f32 v[60:61], v[60:61], 1.0 op_sel_hi:[1,0]
	s_nop 0
	v_rcp_f32_e32 v60, v60
	v_rcp_f32_e32 v61, v61
	s_nop 0
	v_pk_mul_f32 v[50:51], v[50:51], v[60:61]
	s_nop 0
	v_cvt_pk_bf16_f32 v60, v50, v51
	v_pk_mul_f32 v[50:51], v[52:53], v[0:1] op_sel_hi:[1,0]
	v_pk_mul_f32 v[52:53], v[56:57], v[68:69] op_sel_hi:[1,0]
	v_exp_f32_e32 v50, v50
	v_exp_f32_e32 v51, v51
	s_nop 0
	v_pk_add_f32 v[50:51], v[50:51], 1.0 op_sel_hi:[1,0]
	s_nop 0
	v_rcp_f32_e32 v50, v50
	v_rcp_f32_e32 v51, v51
	s_nop 0
	v_pk_mul_f32 v[50:51], v[52:53], v[50:51]
	s_nop 0
	v_cvt_pk_bf16_f32 v61, v50, v51
	v_mad_i64_i32 v[50:51], s[2:3], v66, s14, v[132:133]
	global_store_dwordx4 v[50:51], v[58:61], off
	v_add_u32_e32 v50, 0x90, v134
	v_ashrrev_i32_e32 v51, 31, v50
	v_lshl_add_u64 v[52:53], v[50:51], 2, s[0:1]
	s_waitcnt vmcnt(15)
; __device__ __forceinline__ unsigned pack2(float a, float b) { f32v2_t v = {a, b}; bf16v2_t r = __builtin_convertvector(v, bf16v2_t); return __builtin_bit_cast(unsigned, r); }
; template <int EPI, int N, int K>
; __device__ __forceinline__ void gemm_phase(const KP& p, int l, const bfr* A, const bfr* Bt) {
;     ...
;     if (EPI == 1) {
;       bfr* act = (bfr*)(p.ws + OFF_U);
; #pragma unroll
;       for (int ai = 0; ai < 2; ++ai)
; #pragma unroll
;         for (int m = 0; m < 4; ++m) {
;           int row = erow + ai * HM + wr * 64 + m * 16 + fr;
;           const float r = rs[row];
;           const float nrl = -1.44269504f * r, r2 = r * r;
;           u32x4 pk;
; #pragma unroll
;           for (int bj = 0; bj < 2; ++bj)
; #pragma unroll
;             for (int jj = 0; jj < 2; ++jj) {
;               f32v2_t g2 = {acc[ai][bj][m][0][2 * jj], acc[ai][bj][m][0][2 * jj + 1]};
;               f32v2_t u2 = {acc[ai][bj][m][1][2 * jj], acc[ai][bj][m][1][2 * jj + 1]};
;               f32v2_t t2 = g2 * nrl;
;               f32v2_t e2 = {__builtin_amdgcn_exp2f(t2.x), __builtin_amdgcn_exp2f(t2.y)};
;               f32v2_t d2 = e2 + 1.0f;
;               f32v2_t rc = {__builtin_amdgcn_rcpf(d2.x), __builtin_amdgcn_rcpf(d2.y)};
;               f32v2_t o2 = (g2 * u2) * r2 * rc;
;               pk[bj * 2 + jj] = pack2(o2.x, o2.y);
;             }
;           *(u32x4*)(act + (size_t)row * DFF + (ecol >> 1) + wc * 32 + fq * 8) = pk;
;         }
	v_mov_b32_e32 v51, v227
	v_mul_f32_e32 v0, 0xbfb8aa3b, v51
	v_pk_mul_f32 v[54:55], v[42:43], v[0:1] op_sel_hi:[1,0]
	v_pk_mul_f32 v[44:45], v[44:45], v[0:1] op_sel_hi:[1,0]
	v_exp_f32_e32 v54, v54
	v_exp_f32_e32 v55, v55
	v_exp_f32_e32 v44, v44
	v_exp_f32_e32 v45, v45
	v_mul_f32_e32 v52, v51, v51
	v_pk_add_f32 v[54:55], v[54:55], 1.0 op_sel_hi:[1,0]
	v_pk_mul_f32 v[42:43], v[42:43], v[46:47]
	v_pk_add_f32 v[44:45], v[44:45], 1.0 op_sel_hi:[1,0]
	v_rcp_f32_e32 v54, v54
	v_rcp_f32_e32 v55, v55
	v_rcp_f32_e32 v44, v44
	v_rcp_f32_e32 v45, v45
	v_pk_mul_f32 v[42:43], v[42:43], v[52:53] op_sel_hi:[1,0]
	v_pk_mul_f32 v[46:47], v[48:49], v[52:53] op_sel_hi:[1,0]
	v_pk_mul_f32 v[42:43], v[42:43], v[54:55]
	v_pk_mul_f32 v[44:45], v[46:47], v[44:45]
	v_cvt_pk_bf16_f32 v42, v42, v43
	v_cvt_pk_bf16_f32 v43, v44, v45
	v_pk_mul_f32 v[44:45], v[34:35], v[0:1] op_sel_hi:[1,0]
	v_pk_mul_f32 v[34:35], v[34:35], v[38:39]
	v_exp_f32_e32 v44, v44
	v_exp_f32_e32 v45, v45
	v_pk_mul_f32 v[34:35], v[34:35], v[52:53] op_sel_hi:[1,0]
	v_pk_add_f32 v[44:45], v[44:45], 1.0 op_sel_hi:[1,0]
	s_nop 0
	v_rcp_f32_e32 v44, v44
	v_rcp_f32_e32 v45, v45
	s_nop 0
	v_pk_mul_f32 v[34:35], v[34:35], v[44:45]
	s_nop 0
	v_cvt_pk_bf16_f32 v44, v34, v35
	v_pk_mul_f32 v[34:35], v[36:37], v[0:1] op_sel_hi:[1,0]
	v_pk_mul_f32 v[36:37], v[40:41], v[52:53] op_sel_hi:[1,0]
	v_exp_f32_e32 v34, v34
	v_exp_f32_e32 v35, v35
	s_nop 0
	v_pk_add_f32 v[34:35], v[34:35], 1.0 op_sel_hi:[1,0]
	s_nop 0
	v_rcp_f32_e32 v34, v34
	v_rcp_f32_e32 v35, v35
	s_nop 0
	v_pk_mul_f32 v[34:35], v[36:37], v[34:35]
	s_nop 0
	v_cvt_pk_bf16_f32 v45, v34, v35
	v_mad_i64_i32 v[34:35], s[2:3], v50, s14, v[132:133]
	global_store_dwordx4 v[34:35], v[42:45], off
	v_add_u32_e32 v34, 0xa0, v134
	v_ashrrev_i32_e32 v35, 31, v34
	v_lshl_add_u64 v[36:37], v[34:35], 2, s[0:1]
	s_waitcnt vmcnt(15)
	v_mov_b32_e32 v35, v228
	v_mul_f32_e32 v0, 0xbfb8aa3b, v35
	v_pk_mul_f32 v[38:39], v[26:27], v[0:1] op_sel_hi:[1,0]
	v_pk_mul_f32 v[28:29], v[28:29], v[0:1] op_sel_hi:[1,0]
	v_exp_f32_e32 v38, v38
	v_exp_f32_e32 v39, v39
	v_exp_f32_e32 v28, v28
	v_exp_f32_e32 v29, v29
	v_mul_f32_e32 v36, v35, v35
	v_pk_add_f32 v[38:39], v[38:39], 1.0 op_sel_hi:[1,0]
	v_pk_mul_f32 v[26:27], v[26:27], v[30:31]
	v_pk_add_f32 v[28:29], v[28:29], 1.0 op_sel_hi:[1,0]
	v_rcp_f32_e32 v38, v38
	v_rcp_f32_e32 v39, v39
	v_rcp_f32_e32 v28, v28
	v_rcp_f32_e32 v29, v29
	v_pk_mul_f32 v[26:27], v[26:27], v[36:37] op_sel_hi:[1,0]
	v_pk_mul_f32 v[30:31], v[32:33], v[36:37] op_sel_hi:[1,0]
	v_pk_mul_f32 v[26:27], v[26:27], v[38:39]
	v_pk_mul_f32 v[28:29], v[30:31], v[28:29]
	v_cvt_pk_bf16_f32 v26, v26, v27
	v_cvt_pk_bf16_f32 v27, v28, v29
	v_pk_mul_f32 v[28:29], v[18:19], v[0:1] op_sel_hi:[1,0]
	v_pk_mul_f32 v[18:19], v[18:19], v[22:23]
	v_exp_f32_e32 v28, v28
	v_exp_f32_e32 v29, v29
	v_pk_mul_f32 v[18:19], v[18:19], v[36:37] op_sel_hi:[1,0]
	v_pk_add_f32 v[28:29], v[28:29], 1.0 op_sel_hi:[1,0]
	s_nop 0
	v_rcp_f32_e32 v28, v28
	v_rcp_f32_e32 v29, v29
	s_nop 0
	v_pk_mul_f32 v[18:19], v[18:19], v[28:29]
	s_nop 0
	v_cvt_pk_bf16_f32 v28, v18, v19
	v_pk_mul_f32 v[18:19], v[20:21], v[0:1] op_sel_hi:[1,0]
	v_pk_mul_f32 v[20:21], v[24:25], v[36:37] op_sel_hi:[1,0]
	v_exp_f32_e32 v18, v18
	v_exp_f32_e32 v19, v19
	s_nop 0
	v_pk_add_f32 v[18:19], v[18:19], 1.0 op_sel_hi:[1,0]
	s_nop 0
	v_rcp_f32_e32 v18, v18
	v_rcp_f32_e32 v19, v19
	s_nop 0
	v_pk_mul_f32 v[18:19], v[20:21], v[18:19]
	s_nop 0
	v_cvt_pk_bf16_f32 v29, v18, v19
	v_mad_i64_i32 v[18:19], s[2:3], v34, s14, v[132:133]
	global_store_dwordx4 v[18:19], v[26:29], off
	v_add_u32_e32 v18, 0xb0, v134
	v_ashrrev_i32_e32 v19, 31, v18
	v_lshl_add_u64 v[20:21], v[18:19], 2, s[0:1]
	s_waitcnt vmcnt(15)
	v_mov_b32_e32 v19, v229
	v_mul_f32_e32 v0, 0xbfb8aa3b, v19
	v_pk_mul_f32 v[22:23], v[10:11], v[0:1] op_sel_hi:[1,0]
	v_pk_mul_f32 v[12:13], v[12:13], v[0:1] op_sel_hi:[1,0]
	v_exp_f32_e32 v22, v22
	v_exp_f32_e32 v23, v23
	v_exp_f32_e32 v12, v12
	v_exp_f32_e32 v13, v13
	v_mul_f32_e32 v20, v19, v19
	v_pk_add_f32 v[22:23], v[22:23], 1.0 op_sel_hi:[1,0]
	v_pk_mul_f32 v[10:11], v[10:11], v[14:15]
	v_pk_add_f32 v[12:13], v[12:13], 1.0 op_sel_hi:[1,0]
	v_rcp_f32_e32 v22, v22
	v_rcp_f32_e32 v23, v23
	v_rcp_f32_e32 v12, v12
	v_rcp_f32_e32 v13, v13
	v_pk_mul_f32 v[10:11], v[10:11], v[20:21] op_sel_hi:[1,0]
	v_pk_mul_f32 v[14:15], v[16:17], v[20:21] op_sel_hi:[1,0]
	v_pk_mul_f32 v[10:11], v[10:11], v[22:23]
	v_pk_mul_f32 v[12:13], v[14:15], v[12:13]
	v_cvt_pk_bf16_f32 v10, v10, v11
	v_cvt_pk_bf16_f32 v11, v12, v13
	v_pk_mul_f32 v[12:13], v[2:3], v[0:1] op_sel_hi:[1,0]
	v_pk_mul_f32 v[2:3], v[2:3], v[6:7]
	v_exp_f32_e32 v12, v12
	v_exp_f32_e32 v13, v13
	v_pk_mul_f32 v[2:3], v[2:3], v[20:21] op_sel_hi:[1,0]
	v_pk_add_f32 v[12:13], v[12:13], 1.0 op_sel_hi:[1,0]
	s_nop 0
	v_rcp_f32_e32 v12, v12
	v_rcp_f32_e32 v13, v13
	s_nop 0
	v_pk_mul_f32 v[2:3], v[2:3], v[12:13]
	s_nop 0
	v_cvt_pk_bf16_f32 v12, v2, v3
	v_pk_mul_f32 v[2:3], v[4:5], v[0:1] op_sel_hi:[1,0]
	v_pk_mul_f32 v[4:5], v[8:9], v[20:21] op_sel_hi:[1,0]
	v_exp_f32_e32 v2, v2
	v_exp_f32_e32 v3, v3
	s_nop 0
	v_pk_add_f32 v[2:3], v[2:3], 1.0 op_sel_hi:[1,0]
	s_nop 0
	v_rcp_f32_e32 v2, v2
	v_rcp_f32_e32 v3, v3
	s_nop 0
	v_pk_mul_f32 v[2:3], v[4:5], v[2:3]
	s_nop 0
	v_cvt_pk_bf16_f32 v13, v2, v3
	v_mad_i64_i32 v[2:3], s[2:3], v18, s14, v[132:133]
	global_store_dwordx4 v[2:3], v[10:13], off
	s_cbranch_vccz .LBB0_1151

; #define STAGE_A(P, BASE, br, kt) STAGE_B(P, BASE, br, kt)
; template <int EPI, int N, int K>
; __device__ __forceinline__ void gemm_phase(const KP& p, int l, const bfr* A, const bfr* Bt) {
;     ...
;     if (Lt + p.nblk < nwg) {
;       TILE_COORDS(Lt + p.nblk, brow, bcol, pn);
;       STAGE_B(SB(0, 0), Bt, bcol, 0); STAGE_A(SA(0, 0), A, brow, 0);
;       STAGE_B(SB(0, 1), Bt, bcol + HALF, 0); STAGE_A(SA(0, 1), A, brow + HM, 0);
;     }
;     const float* rs = (const float*)(p.ws + OFF_RS);
;     if (EPI == 1) {
;       bfr* act = (bfr*)(p.ws + OFF_U);
; #pragma unroll
;       for (int ai = 0; ai < 2; ++ai)
; #pragma unroll
;         for (int m = 0; m < 4; ++m) {
;           int row = erow + ai * HM + wr * 64 + m * 16 + fr;
;           const float r = rs[row];
.LBB0_1148:
	s_or_b64 exec, exec, s[36:37]
	v_add_u32_e32 v230, s46, v147
	v_ashrrev_i32_e32 v231, 31, v230
	v_lshl_add_u64 v[230:231], v[230:231], 2, s[0:1]
	global_load_dword v222, v[230:231], off
	global_load_dword v223, v[230:231], off offset:64
	global_load_dword v224, v[230:231], off offset:128
	global_load_dword v225, v[230:231], off offset:192
	global_load_dword v226, v[230:231], off offset:512
	global_load_dword v227, v[230:231], off offset:576
	global_load_dword v228, v[230:231], off offset:640
	global_load_dword v229, v[230:231], off offset:704
	v_readlane_b32 s2, v255, 43
	s_add_i32 s33, s33, s2
	s_cmpk_gt_i32 s33, 0xb57
	s_cselect_b64 s[42:43], -1, 0
	s_and_b64 vcc, exec, s[42:43]
	s_mov_b32 s36, s50
	s_mov_b32 s44, s46
	v_readlane_b32 s3, v255, 44
	s_cbranch_vccnz .Lepi1b_nonext
	s_ashr_i32 s2, s33, 31
	s_lshr_b32 s2, s2, 29
	s_add_i32 s2, s33, s2
	s_ashr_i32 s3, s2, 3
	s_and_b32 s2, s2, -8
	s_sub_i32 s2, s33, s2
	s_cmp_lt_i32 s2, 0
	s_movk_i32 s14, 0x16c
	s_cselect_b32 s14, s14, 0x16b
	s_mul_i32 s2, s14, s2
	s_add_i32 s2, s2, s3
	s_mul_hi_i32 s3, s2, 0x2e8ba2e9
	s_lshr_b32 s14, s3, 31
	s_ashr_i32 s3, s3, 5
	s_add_i32 s3, s3, s14
	s_lshl_b32 s14, s3, 3
	s_sub_i32 s15, 0x84, s14
	s_min_u32 s15, s15, 8
	s_mulk_i32 s3, 0xb0
	s_sub_i32 s36, s2, s3
	v_cvt_f32_ubyte0_e32 v132, s15
	v_cvt_f32_i32_e32 v0, s36
	v_rcp_iflag_f32_e32 v133, v132
	s_ashr_i32 s2, s36, 30
	s_or_b32 s37, s2, 1
	v_readlane_b32 s18, v255, 58
	v_mul_f32_e32 v133, v0, v133
	v_trunc_f32_e32 v133, v133
	v_fma_f32 v0, -v133, v132, v0
	v_cvt_i32_f32_e32 v133, v133
	v_cmp_ge_f32_e64 s[2:3], |v0|, v132
	s_and_b64 s[2:3], s[2:3], exec
	s_cselect_b32 s2, s37, 0
	v_readfirstlane_b32 s3, v133
	s_add_i32 s2, s3, s2
	s_sext_i32_i16 s3, s2
	s_mul_i32 s2, s2, s15
	s_sub_i32 s2, s36, s2
	s_sext_i32_i16 s2, s2
	s_lshl_b32 s36, s3, 8
	s_add_i32 s14, s14, s2
	s_ashr_i32 s37, s36, 31
	s_lshl_b32 s44, s14, 8
	s_lshl_b64 s[2:3], s[36:37], 11
	v_readlane_b32 s15, v255, 57
	s_add_u32 s2, s15, s2
	v_readfirstlane_b32 s14, v139
	s_addc_u32 s3, s18, s3
	v_mov_b32_e32 v0, v137
	v_mov_b32_e32 v132, v138
	s_mov_b32 m0, s14
	v_readfirstlane_b32 s14, v140
	s_ashr_i32 s45, s44, 31
	global_load_lds_dwordx4 v0, s[2:3]
	s_mov_b32 m0, s14
	v_readlane_b32 s16, v255, 45
	global_load_lds_dwordx4 v132, s[2:3]
	s_lshl_b64 s[2:3], s[44:45], 11
	v_readlane_b32 s17, v255, 46
	s_add_u32 s2, s16, s2
	v_readfirstlane_b32 s14, v141
	s_addc_u32 s3, s17, s3
	v_mov_b32_e32 v0, v137
	v_mov_b32_e32 v132, v138
	s_mov_b32 m0, s14
	v_readfirstlane_b32 s14, v142
	s_nop 0
	global_load_lds_dwordx4 v0, s[2:3]
	s_mov_b32 m0, s14
	v_readfirstlane_b32 s14, v143
	global_load_lds_dwordx4 v132, s[2:3]
	s_or_b32 s2, s36, 0x80
	s_ashr_i32 s3, s2, 31
	s_lshl_b64 s[2:3], s[2:3], 11
	s_add_u32 s2, s15, s2
	s_addc_u32 s3, s18, s3
	v_mov_b32_e32 v0, v138
	v_mov_b32_e32 v132, v137
	s_mov_b32 m0, s14
	v_readfirstlane_b32 s14, v144
	s_nop 0
	global_load_lds_dwordx4 v132, s[2:3]
	s_mov_b32 m0, s14
	v_readfirstlane_b32 s14, v145
	global_load_lds_dwordx4 v0, s[2:3]
	s_or_b32 s2, s44, 0x80
	s_ashr_i32 s3, s2, 31
	s_lshl_b64 s[2:3], s[2:3], 11
	s_add_u32 s2, s16, s2
	s_addc_u32 s3, s17, s3
	v_mov_b32_e32 v0, v138
	v_mov_b32_e32 v132, v137
	s_mov_b32 m0, s14
	v_readfirstlane_b32 s14, v146
	s_nop 0
	global_load_lds_dwordx4 v132, s[2:3]
	s_mov_b32 m0, s14
	s_nop 0
	global_load_lds_dwordx4 v0, s[2:3]
	s_branch .LBB0_1141
